# FFN2 weight copies moved from the scan workgroups' tail of phase 6 to the workgroups idle in phase 4's last GEMM round
# speedup vs baseline: 1.0034x; 1.0021x over previous
; #define LAS __attribute__((address_space(3)))
; __device__ __forceinline__ unsigned pk2(float lo, float hi) { f32x2 v = {lo, hi}; bf16x2_t b = __builtin_convertvector(v, bf16x2_t); return __builtin_bit_cast(unsigned, b); }
;     __device__ __forceinline__ const float* in(int i) const { return (const float*)ptr(i); }
;     __device__ __forceinline__ unsigned char* ws() const { return (unsigned char*)ptr(37); }
; #define ws (p.ws())
; __device__ __forceinline__ void transpose_item(const float* W, int K, int N, bf16_t* WT, int k0, int n0, int drow0, LAS float* scr, int lane) {
; #pragma unroll 8
;     for (int i = 0; i < 32; ++i) { const int kk = 2 * i + (lane >> 5); scr[kk * 33 + (lane & 31)] = W[(size_t)(k0 + kk) * N + n0 + (lane & 31)]; }
;     asm volatile("s_waitcnt lgkmcnt(0)" ::: "memory");
;     const int c = lane & 7;
; #pragma unroll
;     for (int j = 0; j < 4; ++j) { const int n = (lane >> 3) + 8 * j; const LAS float* s = scr + (8 * c) * 33 + n;
;         u32x4 o; o.x = pk2(s[0 * 33], s[1 * 33]); o.y = pk2(s[2 * 33], s[3 * 33]); o.z = pk2(s[4 * 33], s[5 * 33]); o.w = pk2(s[6 * 33], s[7 * 33]);
;         *(u32x4*)(WT + (size_t)(drow0 + n) * K + k0 + 8 * c) = o; }
;     asm volatile("s_waitcnt lgkmcnt(0)" ::: "memory");
; __device__ __forceinline__ void ffn2_weights(const Ctx& p, LAS unsigned char* lds) {
;     const int tid = threadIdx.x, lane = tid & 63, wave = __builtin_amdgcn_readfirstlane(tid >> 6);
;     unsigned char* ws = p.ws();
;     LAS float* scr = (LAS float*)(lds + wave * 16384);
;     constexpr int I7 = 16 * 176, I8 = 44 * 32;
;     __syncthreads();
;     for (int it = ((int)blockIdx.x - 128) * 8 + wave; it < I7 + I8; it += 128 * 8) {
;         int r = it;
;         if (r < I7) { const int kb = r / 176, nb = r % 176; transpose_item(p.in(33), DM, NFF, (bf16_t*)(ws + WS_W3T), 64 * kb, 32 * nb, map_w1(32 * nb), scr, lane); continue; } r -= I7;
;         { const int kb = r / 32, nb = r % 32; transpose_item(p.in(34), DFF, DM, (bf16_t*)(ws + WS_W4T), 64 * kb, 32 * nb, 32 * nb, scr, lane); }
;     }
.Llws_done:
.Lp4_ffn2w:
	s_cmpk_lt_u32 s28, 0x55
	s_cbranch_scc1 .Lp4_ffn2w_done
	v_mov_b32_e32 v0, 0x23508
	v_mov_b32_e32 v1, 0x23510
	v_mov_b32_e32 v2, 0x23528
	ds_read_b64 v[4:5], v0
	ds_read_b64 v[6:7], v1
	ds_read_b64 v[8:9], v2
	v_readfirstlane_b32 s2, v180
	s_waitcnt lgkmcnt(0)
	v_readfirstlane_b32 s8, v4
	v_readfirstlane_b32 s9, v5
	v_readfirstlane_b32 s10, v6
	v_readfirstlane_b32 s11, v7
	v_readfirstlane_b32 s12, v8
	v_readfirstlane_b32 s13, v9
	s_nop 4
	s_lshr_b32 s27, s2, 6
	s_sub_u32 s26, s28, 0x55
	s_lshl_b32 s26, s26, 3
	s_add_i32 s26, s26, s27
	s_lshl_b32 s3, s27, 14
	v_and_b32_e32 v0, 63, v180
	v_lshrrev_b32_e32 v1, 3, v0
	v_and_b32_e32 v2, 7, v0
	v_mul_u32_u24_e32 v14, 0x84, v1
	v_lshl_add_u32 v14, v2, 4, v14
	v_add_u32_e32 v14, s3, v14
	v_mul_u32_u24_e32 v15, 0x420, v2
	v_lshl_add_u32 v15, v1, 2, v15
	v_add_u32_e32 v15, s3, v15
	v_mul_u32_u24_e32 v13, 0x5800, v1
	v_lshl_add_u32 v13, v2, 4, v13
	v_lshlrev_b32_e32 v4, 11, v1
	v_lshl_add_u32 v4, v2, 4, v4
	v_add_u32_e32 v5, 0x4000, v4
	v_add_u32_e32 v6, 0x8000, v4
	v_add_u32_e32 v7, 0xc000, v4
	s_add_u32 s18, s12, 0x1f00000
	s_addc_u32 s19, s13, 0
.Lffn2w_w3:
	s_cmpk_gt_u32 s26, 0xaff
	s_cbranch_scc1 .Lffn2w_w3_done
	s_mul_hi_u32 s4, s26, 0x1745d18
	s_mul_i32 s5, s4, 0xb0
	s_sub_u32 s5, s26, s5
	s_mul_i32 s6, s4, 0x160000
	s_lshl_b32 s7, s5, 7
	s_add_u32 s6, s6, s7
	s_add_u32 s14, s8, s6
	s_addc_u32 s15, s9, 0
	s_cmpk_lt_u32 s5, 0x58
	s_cselect_b32 s20, 0, 0x80
	s_cselect_b32 s21, 0, 0x58
	s_sub_u32 s5, s5, s21
	s_lshr_b32 s21, s5, 2
	s_lshl_b32 s21, s21, 8
	s_and_b32 s5, s5, 3
	s_lshl_b32 s5, s5, 5
	s_add_u32 s21, s21, s5
	s_add_u32 s21, s21, s20
	s_lshl_b32 s21, s21, 11
	s_lshl_b32 s4, s4, 7
	s_add_u32 s21, s21, s4
	s_add_u32 s16, s18, s21
	s_addc_u32 s17, s19, 0
	global_load_dwordx4 v[16:19], v13, s[14:15]
	v_add_u32_e32 v12, 0x2c000, v13
	global_load_dwordx4 v[20:23], v12, s[14:15]
	v_add_u32_e32 v12, 0x2c000, v12
	global_load_dwordx4 v[24:27], v12, s[14:15]
	v_add_u32_e32 v12, 0x2c000, v12
	global_load_dwordx4 v[28:31], v12, s[14:15]
	v_add_u32_e32 v12, 0x2c000, v12
	global_load_dwordx4 v[32:35], v12, s[14:15]
	v_add_u32_e32 v12, 0x2c000, v12
	global_load_dwordx4 v[36:39], v12, s[14:15]
	v_add_u32_e32 v12, 0x2c000, v12
	global_load_dwordx4 v[40:43], v12, s[14:15]
	v_add_u32_e32 v12, 0x2c000, v12
	global_load_dwordx4 v[44:47], v12, s[14:15]
	s_waitcnt vmcnt(7)
	ds_write_b32 v14, v16 offset:0
	ds_write_b32 v14, v17 offset:4
	ds_write_b32 v14, v18 offset:8
	ds_write_b32 v14, v19 offset:12
	s_waitcnt vmcnt(6)
	ds_write_b32 v14, v20 offset:1056
	ds_write_b32 v14, v21 offset:1060
	ds_write_b32 v14, v22 offset:1064
	ds_write_b32 v14, v23 offset:1068
	s_waitcnt vmcnt(5)
	ds_write_b32 v14, v24 offset:2112
	ds_write_b32 v14, v25 offset:2116
	ds_write_b32 v14, v26 offset:2120
	ds_write_b32 v14, v27 offset:2124
	s_waitcnt vmcnt(4)
	ds_write_b32 v14, v28 offset:3168
	ds_write_b32 v14, v29 offset:3172
	ds_write_b32 v14, v30 offset:3176
	ds_write_b32 v14, v31 offset:3180
	s_waitcnt vmcnt(3)
	ds_write_b32 v14, v32 offset:4224
	ds_write_b32 v14, v33 offset:4228
	ds_write_b32 v14, v34 offset:4232
	ds_write_b32 v14, v35 offset:4236
	s_waitcnt vmcnt(2)
	ds_write_b32 v14, v36 offset:5280
	ds_write_b32 v14, v37 offset:5284
	ds_write_b32 v14, v38 offset:5288
	ds_write_b32 v14, v39 offset:5292
	s_waitcnt vmcnt(1)
	ds_write_b32 v14, v40 offset:6336
	ds_write_b32 v14, v41 offset:6340
	ds_write_b32 v14, v42 offset:6344
	ds_write_b32 v14, v43 offset:6348
	s_waitcnt vmcnt(0)
	ds_write_b32 v14, v44 offset:7392
	ds_write_b32 v14, v45 offset:7396
	ds_write_b32 v14, v46 offset:7400
	ds_write_b32 v14, v47 offset:7404
	s_waitcnt lgkmcnt(0)
	ds_read2_b32 v[80:81], v15 offset0:0 offset1:33
	ds_read2_b32 v[82:83], v15 offset0:66 offset1:99
	ds_read2_b32 v[84:85], v15 offset0:132 offset1:165
	ds_read2_b32 v[86:87], v15 offset0:198 offset1:231
	ds_read2_b32 v[88:89], v15 offset0:8 offset1:41
	ds_read2_b32 v[90:91], v15 offset0:74 offset1:107
	ds_read2_b32 v[92:93], v15 offset0:140 offset1:173
	ds_read2_b32 v[94:95], v15 offset0:206 offset1:239
	s_waitcnt lgkmcnt(4)
	v_cvt_pk_bf16_f32 v112, v80, v81
	v_cvt_pk_bf16_f32 v113, v82, v83
	v_cvt_pk_bf16_f32 v114, v84, v85
	v_cvt_pk_bf16_f32 v115, v86, v87
	global_store_dwordx4 v4, v[112:115], s[16:17]
	s_waitcnt lgkmcnt(0)
	v_cvt_pk_bf16_f32 v116, v88, v89
	v_cvt_pk_bf16_f32 v117, v90, v91
	v_cvt_pk_bf16_f32 v118, v92, v93
	v_cvt_pk_bf16_f32 v119, v94, v95
	global_store_dwordx4 v5, v[116:119], s[16:17]
	ds_read2_b32 v[96:97], v15 offset0:16 offset1:49
	ds_read2_b32 v[98:99], v15 offset0:82 offset1:115
	ds_read2_b32 v[100:101], v15 offset0:148 offset1:181
	ds_read2_b32 v[102:103], v15 offset0:214 offset1:247
	ds_read2_b32 v[104:105], v15 offset0:24 offset1:57
	ds_read2_b32 v[106:107], v15 offset0:90 offset1:123
	ds_read2_b32 v[108:109], v15 offset0:156 offset1:189
	ds_read2_b32 v[110:111], v15 offset0:222 offset1:255
	s_waitcnt lgkmcnt(4)
	v_cvt_pk_bf16_f32 v120, v96, v97
	v_cvt_pk_bf16_f32 v121, v98, v99
	v_cvt_pk_bf16_f32 v122, v100, v101
	v_cvt_pk_bf16_f32 v123, v102, v103
	global_store_dwordx4 v6, v[120:123], s[16:17]
	s_waitcnt lgkmcnt(0)
	v_cvt_pk_bf16_f32 v124, v104, v105
	v_cvt_pk_bf16_f32 v125, v106, v107
	v_cvt_pk_bf16_f32 v126, v108, v109
	v_cvt_pk_bf16_f32 v127, v110, v111
	global_store_dwordx4 v7, v[124:127], s[16:17]
	s_addk_i32 s26, 0x558
	s_branch .Lffn2w_w3

; #define LAS __attribute__((address_space(3)))
; __device__ __forceinline__ unsigned pk2(float lo, float hi) { f32x2 v = {lo, hi}; bf16x2_t b = __builtin_convertvector(v, bf16x2_t); return __builtin_bit_cast(unsigned, b); }
;     __device__ __forceinline__ const float* in(int i) const { return (const float*)ptr(i); }
;     __device__ __forceinline__ unsigned char* ws() const { return (unsigned char*)ptr(37); }
; #define ws (p.ws())
; __device__ __forceinline__ void transpose_item(const float* W, int K, int N, bf16_t* WT, int k0, int n0, int drow0, LAS float* scr, int lane) {
; #pragma unroll 8
;     for (int i = 0; i < 32; ++i) { const int kk = 2 * i + (lane >> 5); scr[kk * 33 + (lane & 31)] = W[(size_t)(k0 + kk) * N + n0 + (lane & 31)]; }
;     asm volatile("s_waitcnt lgkmcnt(0)" ::: "memory");
;     const int c = lane & 7;
; #pragma unroll
;     for (int j = 0; j < 4; ++j) { const int n = (lane >> 3) + 8 * j; const LAS float* s = scr + (8 * c) * 33 + n;
;         u32x4 o; o.x = pk2(s[0 * 33], s[1 * 33]); o.y = pk2(s[2 * 33], s[3 * 33]); o.z = pk2(s[4 * 33], s[5 * 33]); o.w = pk2(s[6 * 33], s[7 * 33]);
;         *(u32x4*)(WT + (size_t)(drow0 + n) * K + k0 + 8 * c) = o; }
;     asm volatile("s_waitcnt lgkmcnt(0)" ::: "memory");
; __device__ __forceinline__ void ffn2_weights(const Ctx& p, LAS unsigned char* lds) {
;     ...
;     for (int it = ((int)blockIdx.x - 128) * 8 + wave; it < I7 + I8; it += 128 * 8) {
;         int r = it;
;         if (r < I7) { const int kb = r / 176, nb = r % 176; transpose_item(p.in(33), DM, NFF, (bf16_t*)(ws + WS_W3T), 64 * kb, 32 * nb, map_w1(32 * nb), scr, lane); continue; } r -= I7;
;         { const int kb = r / 32, nb = r % 32; transpose_item(p.in(34), DFF, DM, (bf16_t*)(ws + WS_W4T), 64 * kb, 32 * nb, 32 * nb, scr, lane); }
;     }
.Lffn2w_w4:
	s_cmpk_gt_u32 s26, 0x57f
	s_cbranch_scc1 .Lp4_ffn2w_done
	s_lshr_b32 s4, s26, 5
	s_and_b32 s5, s26, 31
	s_lshl_b32 s6, s4, 18
	s_lshl_b32 s7, s5, 7
	s_add_u32 s6, s6, s7
	s_add_u32 s14, s10, s6
	s_addc_u32 s15, s11, 0
	s_mul_i32 s21, s5, 0x2c000
	s_lshl_b32 s4, s4, 7
	s_add_u32 s21, s21, s4
	s_add_u32 s16, s18, s21
	s_addc_u32 s17, s19, 0
	global_load_dwordx4 v[16:19], v13, s[14:15]
	v_add_u32_e32 v12, 0x8000, v13
	global_load_dwordx4 v[20:23], v12, s[14:15]
	v_add_u32_e32 v12, 0x8000, v12
	global_load_dwordx4 v[24:27], v12, s[14:15]
	v_add_u32_e32 v12, 0x8000, v12
	global_load_dwordx4 v[28:31], v12, s[14:15]
	v_add_u32_e32 v12, 0x8000, v12
	global_load_dwordx4 v[32:35], v12, s[14:15]
	v_add_u32_e32 v12, 0x8000, v12
	global_load_dwordx4 v[36:39], v12, s[14:15]
	v_add_u32_e32 v12, 0x8000, v12
	global_load_dwordx4 v[40:43], v12, s[14:15]
	v_add_u32_e32 v12, 0x8000, v12
	global_load_dwordx4 v[44:47], v12, s[14:15]
	s_waitcnt vmcnt(7)
	ds_write_b32 v14, v16 offset:0
	ds_write_b32 v14, v17 offset:4
	ds_write_b32 v14, v18 offset:8
	ds_write_b32 v14, v19 offset:12
	s_waitcnt vmcnt(6)
	ds_write_b32 v14, v20 offset:1056
	ds_write_b32 v14, v21 offset:1060
	ds_write_b32 v14, v22 offset:1064
	ds_write_b32 v14, v23 offset:1068
	s_waitcnt vmcnt(5)
	ds_write_b32 v14, v24 offset:2112
	ds_write_b32 v14, v25 offset:2116
	ds_write_b32 v14, v26 offset:2120
	ds_write_b32 v14, v27 offset:2124
	s_waitcnt vmcnt(4)
	ds_write_b32 v14, v28 offset:3168
	ds_write_b32 v14, v29 offset:3172
	ds_write_b32 v14, v30 offset:3176
	ds_write_b32 v14, v31 offset:3180
	s_waitcnt vmcnt(3)
	ds_write_b32 v14, v32 offset:4224
	ds_write_b32 v14, v33 offset:4228
	ds_write_b32 v14, v34 offset:4232
	ds_write_b32 v14, v35 offset:4236
	s_waitcnt vmcnt(2)
	ds_write_b32 v14, v36 offset:5280
	ds_write_b32 v14, v37 offset:5284
	ds_write_b32 v14, v38 offset:5288
	ds_write_b32 v14, v39 offset:5292
	s_waitcnt vmcnt(1)
	ds_write_b32 v14, v40 offset:6336
	ds_write_b32 v14, v41 offset:6340
	ds_write_b32 v14, v42 offset:6344
	ds_write_b32 v14, v43 offset:6348
	s_waitcnt vmcnt(0)
	ds_write_b32 v14, v44 offset:7392
	ds_write_b32 v14, v45 offset:7396
	ds_write_b32 v14, v46 offset:7400
	ds_write_b32 v14, v47 offset:7404
	s_waitcnt lgkmcnt(0)
	ds_read2_b32 v[80:81], v15 offset0:0 offset1:33
	ds_read2_b32 v[82:83], v15 offset0:66 offset1:99
	ds_read2_b32 v[84:85], v15 offset0:132 offset1:165
	ds_read2_b32 v[86:87], v15 offset0:198 offset1:231
	ds_read2_b32 v[88:89], v15 offset0:8 offset1:41
	ds_read2_b32 v[90:91], v15 offset0:74 offset1:107
	ds_read2_b32 v[92:93], v15 offset0:140 offset1:173
	ds_read2_b32 v[94:95], v15 offset0:206 offset1:239
	s_waitcnt lgkmcnt(4)
	v_cvt_pk_bf16_f32 v112, v80, v81
	v_cvt_pk_bf16_f32 v113, v82, v83
	v_cvt_pk_bf16_f32 v114, v84, v85
	v_cvt_pk_bf16_f32 v115, v86, v87
	global_store_dwordx4 v4, v[112:115], s[16:17]
	s_waitcnt lgkmcnt(0)
	v_cvt_pk_bf16_f32 v116, v88, v89
	v_cvt_pk_bf16_f32 v117, v90, v91
	v_cvt_pk_bf16_f32 v118, v92, v93
	v_cvt_pk_bf16_f32 v119, v94, v95
	global_store_dwordx4 v5, v[116:119], s[16:17]
	ds_read2_b32 v[96:97], v15 offset0:16 offset1:49
	ds_read2_b32 v[98:99], v15 offset0:82 offset1:115
	ds_read2_b32 v[100:101], v15 offset0:148 offset1:181
	ds_read2_b32 v[102:103], v15 offset0:214 offset1:247
	ds_read2_b32 v[104:105], v15 offset0:24 offset1:57
	ds_read2_b32 v[106:107], v15 offset0:90 offset1:123
	ds_read2_b32 v[108:109], v15 offset0:156 offset1:189
	ds_read2_b32 v[110:111], v15 offset0:222 offset1:255
	s_waitcnt lgkmcnt(4)
	v_cvt_pk_bf16_f32 v120, v96, v97
	v_cvt_pk_bf16_f32 v121, v98, v99
	v_cvt_pk_bf16_f32 v122, v100, v101
	v_cvt_pk_bf16_f32 v123, v102, v103
	global_store_dwordx4 v6, v[120:123], s[16:17]
	s_waitcnt lgkmcnt(0)
	v_cvt_pk_bf16_f32 v124, v104, v105
	v_cvt_pk_bf16_f32 v125, v106, v107
	v_cvt_pk_bf16_f32 v126, v108, v109
	v_cvt_pk_bf16_f32 v127, v110, v111
	global_store_dwordx4 v7, v[124:127], s[16:17]
	s_addk_i32 s26, 0x558
	s_branch .Lffn2w_w4
